# k9 + attention M blocks: hipcc s_nop pads before MFMA removed (per-MFMA counted waits kept)
# speedup vs baseline: 1.0028x; 1.0028x over previous
.LBB0_526:
	s_add_i32 s8, s97, s96
	s_add_i32 s7, s8, -2
	s_cmp_lt_i32 s7, 0
	s_cselect_b64 s[4:5], -1, 0
	s_cmp_le_i32 s95, s68
	s_cselect_b64 s[12:13], -1, 0
	s_or_b64 s[12:13], s[4:5], s[12:13]
	v_cndmask_b32_e64 v0, 0, 1, s[12:13]
	v_cmp_ne_u32_e64 s[4:5], 1, v0
	s_andn2_b64 vcc, exec, s[12:13]
	s_mov_b32 s72, s10
	s_cbranch_vccnz .LBB0_528
	s_mul_i32 s9, s72, 0x6000
	v_add_u32_e32 v0, s9, v193
	ds_read_b128 v[2:5], v0 offset:0
	ds_read_b128 v[6:9], v0 offset:0x2000
	v_add_u32_e32 v14, s9, v195
	ds_read_b128 v[10:13], v14 offset:0
	ds_read_b128 v[210:213], v14 offset:0x2000
	v_add_u32_e32 v15, s9, v197
	ds_read_b128 v[214:217], v15 offset:0
	v_add_u32_e32 v209, s9, v199
	s_waitcnt lgkmcnt(4)
	v_mfma_f32_32x32x16_bf16 v[80:95], v[2:5], v[112:115], 0
	ds_read_b128 v[2:5], v15 offset:0x2000
	s_waitcnt lgkmcnt(4)
	v_mfma_f32_32x32x16_bf16 v[96:111], v[6:9], v[112:115], 0
	ds_read_b128 v[6:9], v209 offset:0
	s_waitcnt lgkmcnt(4)
	v_mfma_f32_32x32x16_bf16 v[80:95], v[10:13], v[116:119], v[80:95]
	ds_read_b128 v[10:13], v209 offset:0x2000
	s_waitcnt lgkmcnt(4)
	v_mfma_f32_32x32x16_bf16 v[96:111], v[210:213], v[116:119], v[96:111]
	ds_read_b128 v[210:213], v0 offset:0x80
	s_waitcnt lgkmcnt(4)
	v_mfma_f32_32x32x16_bf16 v[80:95], v[214:217], v[120:123], v[80:95]
	ds_read_b128 v[214:217], v0 offset:0x2080
	v_add_u32_e32 v0, s9, v194
	s_waitcnt lgkmcnt(4)
	v_mfma_f32_32x32x16_bf16 v[96:111], v[2:5], v[120:123], v[96:111]
	ds_read_b128 v[2:5], v14 offset:0x80
	s_waitcnt lgkmcnt(4)
	v_mfma_f32_32x32x16_bf16 v[80:95], v[6:9], v[124:127], v[80:95]
	ds_read_b128 v[6:9], v14 offset:0x2080
	s_waitcnt lgkmcnt(4)
	v_mfma_f32_32x32x16_bf16 v[96:111], v[10:13], v[124:127], v[96:111]
	ds_read_b128 v[10:13], v15 offset:0x80
	s_waitcnt lgkmcnt(4)
	v_mfma_f32_32x32x16_bf16 v[80:95], v[210:213], v[128:131], v[80:95]
	ds_read_b128 v[210:213], v15 offset:0x2080
	s_waitcnt lgkmcnt(4)
	v_mfma_f32_32x32x16_bf16 v[96:111], v[214:217], v[128:131], v[96:111]
	ds_read_b128 v[214:217], v209 offset:0x80
	s_waitcnt lgkmcnt(4)
	v_mfma_f32_32x32x16_bf16 v[80:95], v[2:5], v[132:135], v[80:95]
	ds_read_b128 v[2:5], v209 offset:0x2080
	s_waitcnt lgkmcnt(4)
	v_mfma_f32_32x32x16_bf16 v[96:111], v[6:9], v[132:135], v[96:111]
	ds_read_b128 v[6:9], v0 offset:0
	ds_read_b128 v[218:221], v169 offset:0
	s_waitcnt lgkmcnt(5)
	v_mfma_f32_32x32x16_bf16 v[80:95], v[10:13], v[136:139], v[80:95]
	ds_read_b128 v[10:13], v0 offset:0x1000
	v_add_u32_e32 v0, s9, v196
	s_waitcnt lgkmcnt(5)
	v_mfma_f32_32x32x16_bf16 v[96:111], v[210:213], v[136:139], v[96:111]
	ds_read_b128 v[210:213], v0 offset:0
	ds_read_b128 v[222:225], v169 offset:0x400
	s_waitcnt lgkmcnt(6)
	v_mfma_f32_32x32x16_bf16 v[80:95], v[214:217], v[140:143], v[80:95]
	ds_read_b128 v[214:217], v0 offset:0x1000
	v_add_u32_e32 v0, s9, v198
	s_waitcnt lgkmcnt(6)
	v_mfma_f32_32x32x16_bf16 v[96:111], v[2:5], v[140:143], v[96:111]
	ds_read_b128 v[2:5], v0 offset:0
	ds_read_b128 v[226:229], v169 offset:0x800
	s_waitcnt lgkmcnt(6)
	v_mfma_f32_32x32x16_bf16 v[80:95], v[6:9], v[218:221], v[80:95]
	ds_read_b128 v[6:9], v0 offset:0x1000
	v_add_u32_e32 v0, s9, v200
	s_waitcnt lgkmcnt(6)
	v_mfma_f32_32x32x16_bf16 v[96:111], v[10:13], v[218:221], v[96:111]
	ds_read_b128 v[10:13], v0 offset:0
	ds_read_b128 v[218:221], v169 offset:0xc00
	s_waitcnt lgkmcnt(6)
	v_mfma_f32_32x32x16_bf16 v[80:95], v[210:213], v[222:225], v[80:95]
	ds_read_b128 v[210:213], v0 offset:0x1000
	s_waitcnt lgkmcnt(6)
	v_mfma_f32_32x32x16_bf16 v[96:111], v[214:217], v[222:225], v[96:111]
	s_waitcnt lgkmcnt(4)
	v_mfma_f32_32x32x16_bf16 v[80:95], v[2:5], v[226:229], v[80:95]
	s_waitcnt lgkmcnt(3)
	v_mfma_f32_32x32x16_bf16 v[96:111], v[6:9], v[226:229], v[96:111]
	s_waitcnt lgkmcnt(1)
	v_mfma_f32_32x32x16_bf16 v[80:95], v[10:13], v[218:221], v[80:95]
	s_waitcnt lgkmcnt(0)
	v_mfma_f32_32x32x16_bf16 v[96:111], v[210:213], v[218:221], v[96:111]
.LBB0_528:
	s_cmp_eq_u32 s96, 2
	s_cbranch_scc1 .LBB0_531
	s_add_i32 s8, s8, -3
	s_cmp_gt_i32 s8, -1
	s_cselect_b64 s[8:9], -1, 0
	s_sub_i32 s10, s95, 64
	s_cmp_gt_i32 s10, s68
	s_cselect_b64 s[10:11], -1, 0
	s_and_b64 s[8:9], s[8:9], s[10:11]
	s_and_b64 vcc, exec, s[8:9]
	s_cbranch_vccnz .LBB0_531
	v_lshl_add_u32 v0, s6, 14, v202
	ds_read_b64_tr_b16 v[2:3], v0 offset:0
	ds_read_b64_tr_b16 v[4:5], v0 offset:0x800
	ds_read_b64_tr_b16 v[6:7], v0 offset:0x1000
	ds_read_b64_tr_b16 v[8:9], v0 offset:0x1800
	ds_read_b64_tr_b16 v[10:11], v0 offset:0x2000
	ds_read_b64_tr_b16 v[12:13], v0 offset:0x2800
	ds_read_b64_tr_b16 v[210:211], v0 offset:0x3000
	ds_read_b64_tr_b16 v[212:213], v0 offset:0x3800
	s_waitcnt lgkmcnt(6)
	v_mfma_f32_32x32x16_bf16 v[64:79], v[2:5], v[156:159], v[64:79]
	ds_read_b64_tr_b16 v[2:3], v0 offset:0x200
	ds_read_b64_tr_b16 v[4:5], v0 offset:0xa00
	s_waitcnt lgkmcnt(6)
	v_mfma_f32_32x32x16_bf16 v[64:79], v[6:9], v[152:155], v[64:79]
	ds_read_b64_tr_b16 v[6:7], v0 offset:0x1200
	ds_read_b64_tr_b16 v[8:9], v0 offset:0x1a00
	s_waitcnt lgkmcnt(6)
	v_mfma_f32_32x32x16_bf16 v[64:79], v[10:13], v[148:151], v[64:79]
	ds_read_b64_tr_b16 v[10:11], v0 offset:0x2200
	ds_read_b64_tr_b16 v[12:13], v0 offset:0x2a00
	s_waitcnt lgkmcnt(6)
	v_mfma_f32_32x32x16_bf16 v[64:79], v[210:213], v[144:147], v[64:79]
	ds_read_b64_tr_b16 v[210:211], v0 offset:0x3200
	ds_read_b64_tr_b16 v[212:213], v0 offset:0x3a00
	s_waitcnt lgkmcnt(6)
	v_mfma_f32_32x32x16_bf16 v[48:63], v[2:5], v[156:159], v[48:63]
	ds_read_b64_tr_b16 v[2:3], v0 offset:0x400
	ds_read_b64_tr_b16 v[4:5], v0 offset:0xc00
	s_waitcnt lgkmcnt(6)
	v_mfma_f32_32x32x16_bf16 v[48:63], v[6:9], v[152:155], v[48:63]
	ds_read_b64_tr_b16 v[6:7], v0 offset:0x1400
	ds_read_b64_tr_b16 v[8:9], v0 offset:0x1c00
	s_waitcnt lgkmcnt(6)
	v_mfma_f32_32x32x16_bf16 v[48:63], v[10:13], v[148:151], v[48:63]
	ds_read_b64_tr_b16 v[10:11], v0 offset:0x2400
	ds_read_b64_tr_b16 v[12:13], v0 offset:0x2c00
	s_waitcnt lgkmcnt(6)
	v_mfma_f32_32x32x16_bf16 v[48:63], v[210:213], v[144:147], v[48:63]
	ds_read_b64_tr_b16 v[210:211], v0 offset:0x3400
	ds_read_b64_tr_b16 v[212:213], v0 offset:0x3c00
	s_waitcnt lgkmcnt(6)
	v_mfma_f32_32x32x16_bf16 v[32:47], v[2:5], v[156:159], v[32:47]
	ds_read_b64_tr_b16 v[2:3], v0 offset:0x600
	ds_read_b64_tr_b16 v[4:5], v0 offset:0xe00
	s_waitcnt lgkmcnt(6)
	v_mfma_f32_32x32x16_bf16 v[32:47], v[6:9], v[152:155], v[32:47]
	ds_read_b64_tr_b16 v[6:7], v0 offset:0x1600
	ds_read_b64_tr_b16 v[8:9], v0 offset:0x1e00
	s_waitcnt lgkmcnt(6)
	v_mfma_f32_32x32x16_bf16 v[32:47], v[10:13], v[148:151], v[32:47]
	ds_read_b64_tr_b16 v[10:11], v0 offset:0x2600
	ds_read_b64_tr_b16 v[12:13], v0 offset:0x2e00
	s_waitcnt lgkmcnt(6)
	v_mfma_f32_32x32x16_bf16 v[32:47], v[210:213], v[144:147], v[32:47]
	ds_read_b64_tr_b16 v[210:211], v0 offset:0x3600
	ds_read_b64_tr_b16 v[212:213], v0 offset:0x3e00
	s_waitcnt lgkmcnt(6)
	v_mfma_f32_32x32x16_bf16 v[16:31], v[2:5], v[156:159], v[16:31]
	s_waitcnt lgkmcnt(4)
	v_mfma_f32_32x32x16_bf16 v[16:31], v[6:9], v[152:155], v[16:31]
	s_waitcnt lgkmcnt(2)
	v_mfma_f32_32x32x16_bf16 v[16:31], v[10:13], v[148:151], v[16:31]
	s_waitcnt lgkmcnt(0)
	v_mfma_f32_32x32x16_bf16 v[16:31], v[210:213], v[144:147], v[16:31]

.LBB0_573:
	s_add_i32 s7, s69, s0
	s_cmp_lt_i32 s7, 0
	s_cselect_b64 s[4:5], -1, 0
	s_add_i32 s8, s68, s86
	s_add_i32 s9, s8, 0xffffff80
	s_cmp_le_i32 s9, s95
	s_cselect_b64 s[10:11], -1, 0
	s_or_b64 s[10:11], s[4:5], s[10:11]
	v_cndmask_b32_e64 v2, 0, 1, s[10:11]
	v_cmp_ne_u32_e64 s[4:5], 1, v2
	s_andn2_b64 vcc, exec, s[10:11]
	s_cbranch_vccnz .LBB0_575
	s_mul_i32 s9, s1, 0x6000
	v_add_u32_e32 v14, s9, v193
	ds_read_b128 v[2:5], v14 offset:0
	ds_read_b128 v[6:9], v14 offset:0x2000
	v_add_u32_e32 v15, s9, v195
	ds_read_b128 v[10:13], v15 offset:0
	ds_read_b128 v[174:177], v15 offset:0x2000
	v_add_u32_e32 v159, s9, v197
	ds_read_b128 v[178:181], v159 offset:0
	v_add_u32_e32 v163, s9, v199
	s_waitcnt lgkmcnt(4)
	v_mfma_f32_32x32x16_bf16 v[96:111], v[2:5], v[112:115], 0
	ds_read_b128 v[2:5], v159 offset:0x2000
	s_waitcnt lgkmcnt(4)
	v_mfma_f32_32x32x16_bf16 v[80:95], v[6:9], v[112:115], 0
	ds_read_b128 v[6:9], v163 offset:0
	s_waitcnt lgkmcnt(4)
	v_mfma_f32_32x32x16_bf16 v[96:111], v[10:13], v[116:119], v[96:111]
	ds_read_b128 v[10:13], v163 offset:0x2000
	s_waitcnt lgkmcnt(4)
	v_mfma_f32_32x32x16_bf16 v[80:95], v[174:177], v[116:119], v[80:95]
	ds_read_b128 v[174:177], v14 offset:0x80
	ds_read_b128 v[208:211], v156 offset:0
	s_waitcnt lgkmcnt(5)
	v_mfma_f32_32x32x16_bf16 v[96:111], v[178:181], v[120:123], v[96:111]
	ds_read_b128 v[178:181], v14 offset:0x2080
	s_waitcnt lgkmcnt(5)
	v_mfma_f32_32x32x16_bf16 v[80:95], v[2:5], v[120:123], v[80:95]
	ds_read_b128 v[2:5], v15 offset:0x80
	ds_read_b128 v[212:215], v156 offset:0x400
	s_waitcnt lgkmcnt(6)
	v_mfma_f32_32x32x16_bf16 v[96:111], v[6:9], v[124:127], v[96:111]
	ds_read_b128 v[6:9], v15 offset:0x2080
	s_waitcnt lgkmcnt(6)
	v_mfma_f32_32x32x16_bf16 v[80:95], v[10:13], v[124:127], v[80:95]
	ds_read_b128 v[10:13], v159 offset:0x80
	ds_read_b128 v[216:219], v156 offset:0x800
	s_waitcnt lgkmcnt(6)
	v_mfma_f32_32x32x16_bf16 v[96:111], v[174:177], v[208:211], v[96:111]
	ds_read_b128 v[174:177], v159 offset:0x2080
	s_waitcnt lgkmcnt(6)
	v_mfma_f32_32x32x16_bf16 v[80:95], v[178:181], v[208:211], v[80:95]
	ds_read_b128 v[178:181], v163 offset:0x80
	ds_read_b128 v[208:211], v156 offset:0xc00
	s_waitcnt lgkmcnt(6)
	v_mfma_f32_32x32x16_bf16 v[96:111], v[2:5], v[212:215], v[96:111]
	ds_read_b128 v[2:5], v163 offset:0x2080
	s_waitcnt lgkmcnt(6)
	v_mfma_f32_32x32x16_bf16 v[80:95], v[6:9], v[212:215], v[80:95]
	s_waitcnt lgkmcnt(4)
	v_mfma_f32_32x32x16_bf16 v[96:111], v[10:13], v[216:219], v[96:111]
	s_waitcnt lgkmcnt(3)
	v_mfma_f32_32x32x16_bf16 v[80:95], v[174:177], v[216:219], v[80:95]
	s_waitcnt lgkmcnt(1)
	v_mfma_f32_32x32x16_bf16 v[96:111], v[178:181], v[208:211], v[96:111]
	s_waitcnt lgkmcnt(0)
	v_mfma_f32_32x32x16_bf16 v[80:95], v[2:5], v[208:211], v[80:95]
.LBB0_575:
	s_cmp_eq_u32 s0, 0
	s_cbranch_scc1 .LBB0_578
	s_add_i32 s9, s7, -1
	s_cmp_gt_i32 s9, -1
	s_cselect_b64 s[10:11], -1, 0
	s_add_i32 s9, s8, 0xffffff40
	s_cmp_gt_i32 s9, s95
	s_cselect_b64 s[12:13], -1, 0
	s_and_b64 s[10:11], s[10:11], s[12:13]
	s_and_b64 vcc, exec, s[10:11]
	s_cbranch_vccnz .LBB0_578
	v_lshl_add_u32 v14, s6, 14, v202
	ds_read_b64_tr_b16 v[2:3], v14 offset:0
	ds_read_b64_tr_b16 v[4:5], v14 offset:0x800
	ds_read_b64_tr_b16 v[6:7], v14 offset:0x1000
	ds_read_b64_tr_b16 v[8:9], v14 offset:0x1800
	ds_read_b64_tr_b16 v[10:11], v14 offset:0x2000
	ds_read_b64_tr_b16 v[12:13], v14 offset:0x2800
	ds_read_b64_tr_b16 v[174:175], v14 offset:0x3000
	ds_read_b64_tr_b16 v[176:177], v14 offset:0x3800
	s_waitcnt lgkmcnt(6)
	v_mfma_f32_32x32x16_bf16 v[64:79], v[2:5], v[140:143], v[64:79]
	ds_read_b64_tr_b16 v[2:3], v14 offset:0x200
	ds_read_b64_tr_b16 v[4:5], v14 offset:0xa00
	s_waitcnt lgkmcnt(6)
	v_mfma_f32_32x32x16_bf16 v[64:79], v[6:9], v[136:139], v[64:79]
	ds_read_b64_tr_b16 v[6:7], v14 offset:0x1200
	ds_read_b64_tr_b16 v[8:9], v14 offset:0x1a00
	s_waitcnt lgkmcnt(6)
	v_mfma_f32_32x32x16_bf16 v[64:79], v[10:13], v[132:135], v[64:79]
	ds_read_b64_tr_b16 v[10:11], v14 offset:0x2200
	ds_read_b64_tr_b16 v[12:13], v14 offset:0x2a00
	s_waitcnt lgkmcnt(6)
	v_mfma_f32_32x32x16_bf16 v[64:79], v[174:177], v[128:131], v[64:79]
	ds_read_b64_tr_b16 v[174:175], v14 offset:0x3200
	ds_read_b64_tr_b16 v[176:177], v14 offset:0x3a00
	s_waitcnt lgkmcnt(6)
	v_mfma_f32_32x32x16_bf16 v[48:63], v[2:5], v[140:143], v[48:63]
	ds_read_b64_tr_b16 v[2:3], v14 offset:0x400
	ds_read_b64_tr_b16 v[4:5], v14 offset:0xc00
	s_waitcnt lgkmcnt(6)
	v_mfma_f32_32x32x16_bf16 v[48:63], v[6:9], v[136:139], v[48:63]
	ds_read_b64_tr_b16 v[6:7], v14 offset:0x1400
	ds_read_b64_tr_b16 v[8:9], v14 offset:0x1c00
	s_waitcnt lgkmcnt(6)
	v_mfma_f32_32x32x16_bf16 v[48:63], v[10:13], v[132:135], v[48:63]
	ds_read_b64_tr_b16 v[10:11], v14 offset:0x2400
	ds_read_b64_tr_b16 v[12:13], v14 offset:0x2c00
	s_waitcnt lgkmcnt(6)
	v_mfma_f32_32x32x16_bf16 v[48:63], v[174:177], v[128:131], v[48:63]
	ds_read_b64_tr_b16 v[174:175], v14 offset:0x3400
	ds_read_b64_tr_b16 v[176:177], v14 offset:0x3c00
	s_waitcnt lgkmcnt(6)
	v_mfma_f32_32x32x16_bf16 v[32:47], v[2:5], v[140:143], v[32:47]
	ds_read_b64_tr_b16 v[2:3], v14 offset:0x600
	ds_read_b64_tr_b16 v[4:5], v14 offset:0xe00
	s_waitcnt lgkmcnt(6)
	v_mfma_f32_32x32x16_bf16 v[32:47], v[6:9], v[136:139], v[32:47]
	ds_read_b64_tr_b16 v[6:7], v14 offset:0x1600
	ds_read_b64_tr_b16 v[8:9], v14 offset:0x1e00
	s_waitcnt lgkmcnt(6)
	v_mfma_f32_32x32x16_bf16 v[32:47], v[10:13], v[132:135], v[32:47]
	ds_read_b64_tr_b16 v[10:11], v14 offset:0x2600
	ds_read_b64_tr_b16 v[12:13], v14 offset:0x2e00
	s_waitcnt lgkmcnt(6)
	v_mfma_f32_32x32x16_bf16 v[32:47], v[174:177], v[128:131], v[32:47]
	ds_read_b64_tr_b16 v[174:175], v14 offset:0x3600
	ds_read_b64_tr_b16 v[176:177], v14 offset:0x3e00
	s_waitcnt lgkmcnt(6)
	v_mfma_f32_32x32x16_bf16 v[16:31], v[2:5], v[140:143], v[16:31]
	s_waitcnt lgkmcnt(4)
	v_mfma_f32_32x32x16_bf16 v[16:31], v[6:9], v[136:139], v[16:31]
	s_waitcnt lgkmcnt(2)
	v_mfma_f32_32x32x16_bf16 v[16:31], v[10:13], v[132:135], v[16:31]
	s_waitcnt lgkmcnt(0)
	v_mfma_f32_32x32x16_bf16 v[16:31], v[174:177], v[128:131], v[16:31]
